# attention: one static s_setprio 1 for the c=0 wave half during the unit
# speedup vs baseline: 1.0028x; 1.0028x over previous
.Lattn_pro_join:
	s_barrier
	ds_read_b128 v[96:99], v182 offset:0
	ds_read_b128 v[100:103], v182 offset:4096
	ds_read_b128 v[104:107], v183 offset:0
	ds_read_b128 v[108:111], v183 offset:4096
	ds_read_b128 v[112:115], v184 offset:0
	ds_read_b128 v[116:119], v184 offset:4096
	ds_read_b128 v[120:123], v185 offset:0
	ds_read_b128 v[124:127], v185 offset:4096
	s_waitcnt lgkmcnt(0)
	v_mfma_f32_32x32x16_bf16 v[64:79], v[96:99], v[128:131], 0
	v_mfma_f32_32x32x16_bf16 v[80:95], v[100:103], v[128:131], 0
	v_mfma_f32_32x32x16_bf16 v[64:79], v[104:107], v[132:135], v[64:79]
	v_mfma_f32_32x32x16_bf16 v[80:95], v[108:111], v[132:135], v[80:95]
	v_mfma_f32_32x32x16_bf16 v[64:79], v[112:115], v[136:139], v[64:79]
	v_mfma_f32_32x32x16_bf16 v[80:95], v[116:119], v[136:139], v[80:95]
	v_mfma_f32_32x32x16_bf16 v[64:79], v[120:123], v[140:143], v[64:79]
	v_mfma_f32_32x32x16_bf16 v[80:95], v[124:127], v[140:143], v[80:95]
	s_waitcnt vmcnt(4)
	s_barrier
	ds_read_b128 v[208:211], v182 offset:16384
	ds_read_b128 v[212:215], v182 offset:20480
	ds_read_b128 v[216:219], v183 offset:16384
	ds_read_b128 v[220:223], v183 offset:20480
	ds_read_b128 v[224:227], v184 offset:16384
	ds_read_b128 v[228:231], v184 offset:20480
	s_nop 7
	s_cmp_lg_u32 s14, 0
	s_cbranch_scc1 .Lattn_sprio
	s_setprio 1

.Lattn_end:
	s_setprio 0
	ds_bpermute_b32 v65, v165, v64
	s_and_b64 vcc, exec, s[28:29]
	s_waitcnt lgkmcnt(0)
	v_add_f32_e32 v64, v64, v65
	s_cbranch_vccz .LBB0_651
	v_div_scale_f32 v65, s[40:41], v64, v64, v177
	v_rcp_f32_e32 v66, v65
	v_div_scale_f32 v67, vcc, v177, v64, v177
	v_fma_f32 v68, -v65, v66, 1.0
	v_fmac_f32_e32 v66, v68, v66
	v_mul_f32_e32 v68, v67, v66
	v_fma_f32 v69, -v65, v68, v67
	v_fmac_f32_e32 v68, v69, v66
	v_fma_f32 v65, -v65, v68, v67
	v_div_fmas_f32 v65, v65, v66, v68
	v_div_fixup_f32 v65, v65, v64, v177
	v_mul_f32_e32 v66, v48, v65
	v_mul_f32_e32 v67, v49, v65
	ds_write2st64_b32 v181, v66, v67 offset1:1
	v_mul_f32_e32 v66, v50, v65
	v_mul_f32_e32 v67, v51, v65
	ds_write2st64_b32 v181, v66, v67 offset0:2 offset1:3
	v_mul_f32_e32 v66, v52, v65
	v_mul_f32_e32 v67, v53, v65
	ds_write2st64_b32 v181, v66, v67 offset0:4 offset1:5
	v_mul_f32_e32 v66, v54, v65
	v_mul_f32_e32 v67, v55, v65
	ds_write2st64_b32 v181, v66, v67 offset0:6 offset1:7
	v_mul_f32_e32 v66, v56, v65
	v_mul_f32_e32 v67, v57, v65
	ds_write2st64_b32 v181, v66, v67 offset0:8 offset1:9
	v_mul_f32_e32 v66, v58, v65
	v_mul_f32_e32 v67, v59, v65
	ds_write2st64_b32 v181, v66, v67 offset0:10 offset1:11
	v_mul_f32_e32 v66, v60, v65
	v_mul_f32_e32 v67, v61, v65
	ds_write2st64_b32 v181, v66, v67 offset0:12 offset1:13
	v_mul_f32_e32 v66, v62, v65
	v_mul_f32_e32 v67, v63, v65
	ds_write2st64_b32 v181, v66, v67 offset0:14 offset1:15
	v_mul_f32_e32 v66, v32, v65
	v_mul_f32_e32 v67, v33, v65
	ds_write2st64_b32 v181, v66, v67 offset0:16 offset1:17
	v_mul_f32_e32 v66, v34, v65
	v_mul_f32_e32 v67, v35, v65
	ds_write2st64_b32 v181, v66, v67 offset0:18 offset1:19
	v_mul_f32_e32 v66, v36, v65
	v_mul_f32_e32 v67, v37, v65
	ds_write2st64_b32 v181, v66, v67 offset0:20 offset1:21
	v_mul_f32_e32 v66, v38, v65
	v_mul_f32_e32 v67, v39, v65
	ds_write2st64_b32 v181, v66, v67 offset0:22 offset1:23
	v_mul_f32_e32 v66, v40, v65
	v_mul_f32_e32 v67, v41, v65
	ds_write2st64_b32 v181, v66, v67 offset0:24 offset1:25
	v_mul_f32_e32 v66, v42, v65
	v_mul_f32_e32 v67, v43, v65
	ds_write2st64_b32 v181, v66, v67 offset0:26 offset1:27
	v_mul_f32_e32 v66, v44, v65
	v_mul_f32_e32 v67, v45, v65
	ds_write2st64_b32 v181, v66, v67 offset0:28 offset1:29
	v_mul_f32_e32 v66, v46, v65
	v_mul_f32_e32 v67, v47, v65
	ds_write2st64_b32 v181, v66, v67 offset0:30 offset1:31
	v_mul_f32_e32 v66, v16, v65
	v_mul_f32_e32 v67, v17, v65
	ds_write2st64_b32 v181, v66, v67 offset0:32 offset1:33
	v_mul_f32_e32 v66, v18, v65
	v_mul_f32_e32 v67, v19, v65
	ds_write2st64_b32 v181, v66, v67 offset0:34 offset1:35
	v_mul_f32_e32 v66, v20, v65
	v_mul_f32_e32 v67, v21, v65
	ds_write2st64_b32 v181, v66, v67 offset0:36 offset1:37
	v_mul_f32_e32 v66, v22, v65
	v_mul_f32_e32 v67, v23, v65
	ds_write2st64_b32 v181, v66, v67 offset0:38 offset1:39
	v_mul_f32_e32 v66, v24, v65
	v_mul_f32_e32 v67, v25, v65
	ds_write2st64_b32 v181, v66, v67 offset0:40 offset1:41
	v_mul_f32_e32 v66, v26, v65
	v_mul_f32_e32 v67, v27, v65
	ds_write2st64_b32 v181, v66, v67 offset0:42 offset1:43
	v_mul_f32_e32 v66, v28, v65
	v_mul_f32_e32 v67, v29, v65
	ds_write2st64_b32 v181, v66, v67 offset0:44 offset1:45
	v_mul_f32_e32 v66, v30, v65
	v_mul_f32_e32 v67, v31, v65
	ds_write2st64_b32 v181, v66, v67 offset0:46 offset1:47
	v_mul_f32_e32 v66, v0, v65
	v_mul_f32_e32 v67, v1, v65
	ds_write2st64_b32 v181, v66, v67 offset0:48 offset1:49
	v_mul_f32_e32 v66, v2, v65
	v_mul_f32_e32 v67, v3, v65
	ds_write2st64_b32 v181, v66, v67 offset0:50 offset1:51
	v_mul_f32_e32 v66, v4, v65
	v_mul_f32_e32 v67, v5, v65
	ds_write2st64_b32 v181, v66, v67 offset0:52 offset1:53
	v_mul_f32_e32 v66, v6, v65
	v_mul_f32_e32 v67, v7, v65
	ds_write2st64_b32 v181, v66, v67 offset0:54 offset1:55
	v_mul_f32_e32 v66, v8, v65
	v_mul_f32_e32 v67, v9, v65
	ds_write2st64_b32 v181, v66, v67 offset0:56 offset1:57
	v_mul_f32_e32 v66, v10, v65
	v_mul_f32_e32 v67, v11, v65
	ds_write2st64_b32 v181, v66, v67 offset0:58 offset1:59
	v_mul_f32_e32 v66, v12, v65
	v_mul_f32_e32 v67, v13, v65
	ds_write2st64_b32 v181, v66, v67 offset0:60 offset1:61
	v_mul_f32_e32 v66, v14, v65
	v_mul_f32_e32 v65, v15, v65
	ds_write2st64_b32 v181, v66, v65 offset0:62 offset1:63
